# grid barrier: XCD leaders poll the cross-XCD arrival counter directly instead of the release flag
# speedup vs baseline: 1.0059x; 1.0059x over previous
.LBB0_205:
	s_or_b64 exec, exec, s[38:39]
	v_cvt_f32_u32_e32 v4, v0
	s_waitcnt vmcnt(0)
	v_readfirstlane_b32 s0, v3
	v_sub_u32_e32 v3, 0, v0
	s_mov_b64 s[38:39], -1
	v_rcp_iflag_f32_e32 v4, v4
	v_add_u32_e32 v2, s0, v2
	v_add_u32_e32 v5, 1, v2
	v_readlane_b32 s0, v253, 8
	v_mul_f32_e32 v4, 0x4f7ffffe, v4
	v_cvt_u32_f32_e32 v4, v4
	v_readlane_b32 s1, v253, 9
	v_mul_lo_u32 v3, v3, v4
	v_mul_hi_u32 v3, v4, v3
	v_add_u32_e32 v3, v4, v3
	v_mul_hi_u32 v3, v2, v3
	v_mul_lo_u32 v4, v3, v0
	v_sub_u32_e32 v2, v2, v4
	v_add_u32_e32 v6, 1, v3
	v_sub_u32_e32 v4, v2, v0
	v_cmp_ge_u32_e32 vcc, v2, v0
	s_nop 1
	v_cndmask_b32_e32 v3, v3, v6, vcc
	v_cndmask_b32_e32 v2, v2, v4, vcc
	v_add_u32_e32 v4, 1, v3
	v_cmp_ge_u32_e32 vcc, v2, v0
	s_nop 1
	v_cndmask_b32_e32 v4, v3, v4, vcc
	v_mul_lo_u32 v2, v0, v4
	v_add_u32_e32 v0, v2, v0
	v_cmp_ne_u32_e32 vcc, v5, v0
	v_mov_b32_e32 v5, v0
	v_mov_b64_e32 v[2:3], s[0:1]
	s_and_saveexec_b64 s[36:37], vcc
	s_cbranch_execz .LBB0_217
	v_readlane_b32 s0, v254, 18
	v_readlane_b32 s1, v254, 19
	s_mov_b64 s[40:41], 0
	s_nop 3
	global_load_dword v0, v1, s[0:1] sc1
	s_waitcnt vmcnt(0)
	v_cmp_lt_u32_e32 vcc, v0, v5
	s_and_saveexec_b64 s[38:39], vcc
	s_cbranch_execz .LBB0_216
	s_mov_b32 s0, 1
	s_branch .LBB0_209

.LBB0_213:
	v_readlane_b32 s2, v254, 18
	v_readlane_b32 s3, v254, 19
	s_add_i32 s0, s0, 1
	s_mov_b64 s[46:47], -1
	s_nop 2
	global_load_dword v0, v1, s[2:3] sc1
	s_waitcnt vmcnt(0)
	v_cmp_ge_u32_e32 vcc, v0, v5
	s_orn2_b64 s[44:45], vcc, exec
	s_branch .LBB0_208

.LBB0_278:
	s_or_b64 exec, exec, s[38:39]
	s_waitcnt vmcnt(0)
	v_readfirstlane_b32 s0, v3
	v_sub_u32_e32 v4, 0, v2
	s_mov_b64 s[38:39], -1
	v_add_u32_e32 v3, s0, v0
	v_cvt_f32_u32_e32 v0, v2
	v_readlane_b32 s0, v253, 8
	v_readlane_b32 s1, v253, 9
	v_rcp_iflag_f32_e32 v0, v0
	s_nop 0
	v_mul_f32_e32 v0, 0x4f7ffffe, v0
	v_cvt_u32_f32_e32 v0, v0
	v_mul_lo_u32 v4, v4, v0
	v_mul_hi_u32 v4, v0, v4
	v_add_u32_e32 v0, v0, v4
	v_mul_hi_u32 v0, v3, v0
	v_mul_lo_u32 v4, v0, v2
	v_sub_u32_e32 v4, v3, v4
	v_cmp_ge_u32_e32 vcc, v4, v2
	v_add_u32_e32 v5, 1, v0
	v_add_u32_e32 v3, 1, v3
	v_cndmask_b32_e32 v0, v0, v5, vcc
	v_sub_u32_e32 v5, v4, v2
	v_cndmask_b32_e32 v4, v4, v5, vcc
	v_cmp_ge_u32_e32 vcc, v4, v2
	v_add_u32_e32 v4, 1, v0
	s_nop 0
	v_cndmask_b32_e32 v0, v0, v4, vcc
	v_mul_lo_u32 v4, v2, v0
	v_add_u32_e32 v2, v4, v2
	v_cmp_ne_u32_e32 vcc, v3, v2
	v_mov_b32_e32 v5, v2
	v_mov_b64_e32 v[2:3], s[0:1]
	s_and_saveexec_b64 s[36:37], vcc
	s_cbranch_execz .LBB0_290
	v_readlane_b32 s0, v254, 18
	v_readlane_b32 s1, v254, 19
	s_mov_b64 s[40:41], 0
	s_nop 3
	global_load_dword v2, v1, s[0:1] sc1
	s_waitcnt vmcnt(0)
	v_cmp_lt_u32_e32 vcc, v2, v5
	s_and_saveexec_b64 s[38:39], vcc
	s_cbranch_execz .LBB0_289
	s_mov_b32 s0, 1
	s_branch .LBB0_282

.LBB0_286:
	v_readlane_b32 s2, v254, 18
	v_readlane_b32 s3, v254, 19
	s_add_i32 s0, s0, 1
	s_mov_b64 s[46:47], -1
	s_nop 2
	global_load_dword v2, v1, s[2:3] sc1
	s_waitcnt vmcnt(0)
	v_cmp_ge_u32_e32 vcc, v2, v5
	s_orn2_b64 s[44:45], vcc, exec
	s_branch .LBB0_281

.LBB0_417:
	s_or_b64 exec, exec, s[40:41]
	s_waitcnt vmcnt(0)
	v_readfirstlane_b32 s0, v3
	v_sub_u32_e32 v4, 0, v2
	s_mov_b64 s[40:41], -1
	v_add_u32_e32 v3, s0, v0
	v_cvt_f32_u32_e32 v0, v2
	v_readlane_b32 s0, v253, 8
	v_readlane_b32 s1, v253, 9
	v_rcp_iflag_f32_e32 v0, v0
	s_nop 0
	v_mul_f32_e32 v0, 0x4f7ffffe, v0
	v_cvt_u32_f32_e32 v0, v0
	v_mul_lo_u32 v4, v4, v0
	v_mul_hi_u32 v4, v0, v4
	v_add_u32_e32 v0, v0, v4
	v_mul_hi_u32 v0, v3, v0
	v_mul_lo_u32 v4, v0, v2
	v_sub_u32_e32 v4, v3, v4
	v_cmp_ge_u32_e32 vcc, v4, v2
	v_add_u32_e32 v5, 1, v0
	v_add_u32_e32 v3, 1, v3
	v_cndmask_b32_e32 v0, v0, v5, vcc
	v_sub_u32_e32 v5, v4, v2
	v_cndmask_b32_e32 v4, v4, v5, vcc
	v_cmp_ge_u32_e32 vcc, v4, v2
	v_add_u32_e32 v4, 1, v0
	s_nop 0
	v_cndmask_b32_e32 v0, v0, v4, vcc
	v_mul_lo_u32 v4, v2, v0
	v_add_u32_e32 v2, v4, v2
	v_cmp_ne_u32_e32 vcc, v3, v2
	v_mov_b32_e32 v5, v2
	v_mov_b64_e32 v[2:3], s[0:1]
	s_and_saveexec_b64 s[38:39], vcc
	s_cbranch_execz .LBB0_429
	v_readlane_b32 s0, v254, 18
	v_readlane_b32 s1, v254, 19
	s_mov_b64 s[42:43], 0
	s_nop 3
	global_load_dword v2, v1, s[0:1] sc1
	s_waitcnt vmcnt(0)
	v_cmp_lt_u32_e32 vcc, v2, v5
	s_and_saveexec_b64 s[40:41], vcc
	s_cbranch_execz .LBB0_428
	s_mov_b32 s0, 1
	s_branch .LBB0_421

.LBB0_425:
	v_readlane_b32 s2, v254, 18
	v_readlane_b32 s3, v254, 19
	s_add_i32 s0, s0, 1
	s_mov_b64 s[52:53], -1
	s_nop 2
	global_load_dword v2, v1, s[2:3] sc1
	s_waitcnt vmcnt(0)
	v_cmp_ge_u32_e32 vcc, v2, v5
	s_orn2_b64 s[46:47], vcc, exec
	s_branch .LBB0_420

.LBB0_928:
	s_or_b64 exec, exec, s[42:43]
	s_waitcnt vmcnt(0)
	v_readfirstlane_b32 s0, v3
	v_sub_u32_e32 v4, 0, v2
	s_mov_b64 s[42:43], -1
	v_add_u32_e32 v3, s0, v0
	v_cvt_f32_u32_e32 v0, v2
	v_readlane_b32 s0, v253, 8
	v_readlane_b32 s1, v253, 9
	v_rcp_iflag_f32_e32 v0, v0
	s_nop 0
	v_mul_f32_e32 v0, 0x4f7ffffe, v0
	v_cvt_u32_f32_e32 v0, v0
	v_mul_lo_u32 v4, v4, v0
	v_mul_hi_u32 v4, v0, v4
	v_add_u32_e32 v0, v0, v4
	v_mul_hi_u32 v0, v3, v0
	v_mul_lo_u32 v4, v0, v2
	v_sub_u32_e32 v4, v3, v4
	v_cmp_ge_u32_e32 vcc, v4, v2
	v_add_u32_e32 v5, 1, v0
	v_add_u32_e32 v3, 1, v3
	v_cndmask_b32_e32 v0, v0, v5, vcc
	v_sub_u32_e32 v5, v4, v2
	v_cndmask_b32_e32 v4, v4, v5, vcc
	v_cmp_ge_u32_e32 vcc, v4, v2
	v_add_u32_e32 v4, 1, v0
	s_nop 0
	v_cndmask_b32_e32 v0, v0, v4, vcc
	v_mul_lo_u32 v4, v2, v0
	v_add_u32_e32 v2, v4, v2
	v_cmp_ne_u32_e32 vcc, v3, v2
	v_mov_b32_e32 v5, v2
	v_mov_b64_e32 v[2:3], s[0:1]
	s_and_saveexec_b64 s[40:41], vcc
	s_cbranch_execz .LBB0_940
	v_readlane_b32 s0, v254, 18
	v_readlane_b32 s1, v254, 19
	s_mov_b64 s[44:45], 0
	s_nop 3
	global_load_dword v2, v1, s[0:1] sc1
	s_waitcnt vmcnt(0)
	v_cmp_lt_u32_e32 vcc, v2, v5
	s_and_saveexec_b64 s[42:43], vcc
	s_cbranch_execz .LBB0_939
	s_mov_b32 s0, 1
	s_branch .LBB0_932

.LBB0_936:
	v_readlane_b32 s2, v254, 18
	v_readlane_b32 s3, v254, 19
	s_add_i32 s0, s0, 1
	s_mov_b64 s[56:57], -1
	s_nop 2
	global_load_dword v2, v1, s[2:3] sc1
	s_waitcnt vmcnt(0)
	v_cmp_ge_u32_e32 vcc, v2, v5
	s_orn2_b64 s[52:53], vcc, exec
	s_branch .LBB0_931
